# acquire hoisting: L1 invalidate (buffer_inv sc1) issued with the arrival atomic instead of after the release poll, on top of v021
# speedup vs baseline: 1.0030x; 1.0030x over previous
; DI unsigned xb_add(unsigned* p, unsigned v) { return __hip_atomic_fetch_add(p, v, __ATOMIC_RELAXED, __HIP_MEMORY_SCOPE_AGENT); }
; DI void xcd_barrier(unsigned* bar, volatile LAS unsigned* st) {
;     ...
;       __builtin_amdgcn_fence(__ATOMIC_ACQUIRE, "agent");
;       xb_add(&bar[XB_XGEN(x)], 1u);
;       asm volatile("s_waitcnt vmcnt(0)" ::: "memory");
.LBB0_320:
	s_or_b64 exec, exec, s[0:1]
	v_mov_b32_e32 v0, s3
	v_add_co_u32_e32 v2, vcc, 0x2000, v0
	v_mov_b32_e32 v0, s2
	s_nop 0
	v_addc_co_u32_e32 v3, vcc, 0, v0, vcc
	s_waitcnt vmcnt(0) lgkmcnt(0)
	flat_atomic_add v[2:3], v187 offset:1024
	s_waitcnt vmcnt(0)

; DI unsigned xb_ld(unsigned* p) { return __hip_atomic_load(p, __ATOMIC_RELAXED, __HIP_MEMORY_SCOPE_AGENT); }
; DI unsigned xb_add(unsigned* p, unsigned v) { return __hip_atomic_fetch_add(p, v, __ATOMIC_RELAXED, __HIP_MEMORY_SCOPE_AGENT); }
; #define XB_SPIN(cond, bar) do { unsigned _sp = 0; while (cond) { __builtin_amdgcn_s_sleep(1); \
;     if ((++_sp & 255u) == 0u) { if (xb_ld(&(bar)[XB_TMO])) break; if (_sp > XB_SPIN_CAP) { atomicAdd(&(bar)[XB_TMO], 1u); break; } } } } while (0)
; DI void xcd_barrier(unsigned* bar, volatile LAS unsigned* st) {
;     ...
;     const unsigned old = xb_add(&bar[XB_XSUB(x)], 1u);
;     const unsigned gen = old / nloc;
;     if (old + 1u == (gen + 1u) * nloc) {
;       __builtin_amdgcn_fence(__ATOMIC_RELEASE, "agent");
;       asm volatile("s_waitcnt vmcnt(0)" ::: "memory");
;       const unsigned og = xb_add(&bar[XB_TOP], 1u);
;       const unsigned tg = og / nx;
;       if (og + 1u == (tg + 1u) * nx) xb_add(&bar[XB_TOPGEN], 1u);
;       else XB_SPIN(xb_ld(&bar[XB_TOPGEN]) == tg, bar);
;       __builtin_amdgcn_fence(__ATOMIC_ACQUIRE, "agent");
;       xb_add(&bar[XB_XGEN(x)], 1u);
;       asm volatile("s_waitcnt vmcnt(0)" ::: "memory");
;     } else {
;       XB_SPIN(xb_ld(&bar[XB_XGEN(x)]) == gen, bar);
.LBB0_350:
	s_lshl_b32 s0, s36, 8
	s_add_u32 s0, s58, s0
	s_addc_u32 s1, s59, 0
	v_mov_b32_e32 v3, s0
	v_add_co_u32_e32 v4, vcc, 0x22f21000, v3
	v_mov_b32_e32 v3, s1
	s_nop 0
	v_addc_co_u32_e32 v5, vcc, 0, v3, vcc
	flat_atomic_add v4, v[4:5], v187 offset:1024 sc0
	buffer_inv sc1
	v_cvt_f32_u32_e32 v3, v2
	v_sub_u32_e32 v5, 0, v2
	s_add_u32 s25, s0, 0x22f20000
	s_addc_u32 s24, s1, 0
	v_rcp_iflag_f32_e32 v3, v3
	s_nop 0
	v_mul_f32_e32 v3, 0x4f7ffffe, v3
	v_cvt_u32_f32_e32 v3, v3
	v_mul_lo_u32 v5, v5, v3
	v_mul_hi_u32 v5, v3, v5
	v_add_u32_e32 v3, v3, v5
	s_waitcnt vmcnt(0) lgkmcnt(0)
	v_mul_hi_u32 v3, v4, v3
	v_mul_lo_u32 v5, v3, v2
	v_sub_u32_e32 v5, v4, v5
	v_cmp_ge_u32_e32 vcc, v5, v2
	v_add_u32_e32 v6, 1, v3
	s_nop 0
	v_cndmask_b32_e32 v3, v3, v6, vcc
	v_sub_u32_e32 v6, v5, v2
	v_cndmask_b32_e32 v5, v5, v6, vcc
	v_cmp_ge_u32_e32 vcc, v5, v2
	v_add_u32_e32 v5, 1, v3
	v_add_u32_e32 v6, 1, v4
	v_cndmask_b32_e32 v3, v3, v5, vcc
	v_mad_u64_u32 v[4:5], s[0:1], v2, v3, v[2:3]
	v_cmp_ne_u32_e32 vcc, v6, v4
	s_and_saveexec_b64 s[0:1], vcc
	s_xor_b64 s[0:1], exec, s[0:1]
	s_cbranch_execz .LBB0_363
	v_mov_b32_e32 v0, s25
	v_add_co_u32_e32 v4, vcc, 0x2000, v0
	v_mov_b32_e32 v0, s24
	s_nop 0
	v_addc_co_u32_e32 v5, vcc, 0, v0, vcc
	flat_load_dword v0, v[4:5] offset:1024 sc1
	s_add_u32 s6, s25, 0x2400
	s_addc_u32 s7, s24, 0
	s_waitcnt vmcnt(0) lgkmcnt(0)
	v_cmp_eq_u32_e32 vcc, v0, v3
	s_and_saveexec_b64 s[4:5], vcc
	s_cbranch_execz .LBB0_362
	s_add_u32 s8, s58, 0x22f20200
	s_addc_u32 s9, s59, 0
	s_mov_b32 s26, 1
	s_mov_b64 s[10:11], 0
	s_branch .LBB0_354

; DI unsigned xb_ld(unsigned* p) { return __hip_atomic_load(p, __ATOMIC_RELAXED, __HIP_MEMORY_SCOPE_AGENT); }
; #define XB_SPIN(cond, bar) do { unsigned _sp = 0; while (cond) { __builtin_amdgcn_s_sleep(1); \
;     if ((++_sp & 255u) == 0u) { if (xb_ld(&(bar)[XB_TMO])) break; if (_sp > XB_SPIN_CAP) { atomicAdd(&(bar)[XB_TMO], 1u); break; } } } } while (0)
; DI void xcd_barrier(unsigned* bar, volatile LAS unsigned* st) {
;     ...
;       XB_SPIN(xb_ld(&bar[XB_XGEN(x)]) == gen, bar);
;       __builtin_amdgcn_fence(__ATOMIC_ACQUIRE, "agent");
;       asm volatile("s_waitcnt vmcnt(0)" ::: "memory");
.LBB0_362:
	s_or_b64 exec, exec, s[4:5]
	s_waitcnt vmcnt(0) lgkmcnt(0)
	s_waitcnt vmcnt(0)

; DI unsigned xb_add(unsigned* p, unsigned v) { return __hip_atomic_fetch_add(p, v, __ATOMIC_RELAXED, __HIP_MEMORY_SCOPE_AGENT); }
; DI void xcd_barrier(unsigned* bar, volatile LAS unsigned* st) {
;     ...
;       __builtin_amdgcn_fence(__ATOMIC_ACQUIRE, "agent");
;       xb_add(&bar[XB_XGEN(x)], 1u);
;       asm volatile("s_waitcnt vmcnt(0)" ::: "memory");
.LBB0_378:
	s_or_b64 exec, exec, s[0:1]
	v_mov_b32_e32 v0, s25
	v_add_co_u32_e32 v2, vcc, 0x2000, v0
	v_mov_b32_e32 v0, s24
	s_nop 0
	v_addc_co_u32_e32 v3, vcc, 0, v0, vcc
	s_waitcnt vmcnt(0) lgkmcnt(0)
	flat_atomic_add v[2:3], v187 offset:1024
	s_waitcnt vmcnt(0)

; DI unsigned xb_ld(unsigned* p) { return __hip_atomic_load(p, __ATOMIC_RELAXED, __HIP_MEMORY_SCOPE_AGENT); }
; DI unsigned xb_add(unsigned* p, unsigned v) { return __hip_atomic_fetch_add(p, v, __ATOMIC_RELAXED, __HIP_MEMORY_SCOPE_AGENT); }
; #define XB_SPIN(cond, bar) do { unsigned _sp = 0; while (cond) { __builtin_amdgcn_s_sleep(1); \
;     if ((++_sp & 255u) == 0u) { if (xb_ld(&(bar)[XB_TMO])) break; if (_sp > XB_SPIN_CAP) { atomicAdd(&(bar)[XB_TMO], 1u); break; } } } } while (0)
; DI void xcd_barrier(unsigned* bar, volatile LAS unsigned* st) {
;     ...
;     const unsigned old = xb_add(&bar[XB_XSUB(x)], 1u);
;     const unsigned gen = old / nloc;
;     if (old + 1u == (gen + 1u) * nloc) {
;       __builtin_amdgcn_fence(__ATOMIC_RELEASE, "agent");
;       asm volatile("s_waitcnt vmcnt(0)" ::: "memory");
;       const unsigned og = xb_add(&bar[XB_TOP], 1u);
;       const unsigned tg = og / nx;
;       if (og + 1u == (tg + 1u) * nx) xb_add(&bar[XB_TOPGEN], 1u);
;       else XB_SPIN(xb_ld(&bar[XB_TOPGEN]) == tg, bar);
;       __builtin_amdgcn_fence(__ATOMIC_ACQUIRE, "agent");
;       xb_add(&bar[XB_XGEN(x)], 1u);
;       asm volatile("s_waitcnt vmcnt(0)" ::: "memory");
;     } else {
;       XB_SPIN(xb_ld(&bar[XB_XGEN(x)]) == gen, bar);
.LBB0_407:
	s_lshl_b32 s0, s2, 8
	s_add_u32 s0, s58, s0
	s_addc_u32 s1, s59, 0
	v_mov_b32_e32 v3, s0
	v_add_co_u32_e32 v4, vcc, 0x22f21000, v3
	v_mov_b32_e32 v3, s1
	s_nop 0
	v_addc_co_u32_e32 v5, vcc, 0, v3, vcc
	flat_atomic_add v4, v[4:5], v187 offset:1024 sc0
	buffer_inv sc1
	v_cvt_f32_u32_e32 v3, v2
	v_sub_u32_e32 v5, 0, v2
	s_add_u32 s3, s0, 0x22f20000
	s_addc_u32 s2, s1, 0
	v_rcp_iflag_f32_e32 v3, v3
	s_nop 0
	v_mul_f32_e32 v3, 0x4f7ffffe, v3
	v_cvt_u32_f32_e32 v3, v3
	v_mul_lo_u32 v5, v5, v3
	v_mul_hi_u32 v5, v3, v5
	v_add_u32_e32 v3, v3, v5
	s_waitcnt vmcnt(0) lgkmcnt(0)
	v_mul_hi_u32 v3, v4, v3
	v_mul_lo_u32 v5, v3, v2
	v_sub_u32_e32 v5, v4, v5
	v_cmp_ge_u32_e32 vcc, v5, v2
	v_add_u32_e32 v6, 1, v3
	s_nop 0
	v_cndmask_b32_e32 v3, v3, v6, vcc
	v_sub_u32_e32 v6, v5, v2
	v_cndmask_b32_e32 v5, v5, v6, vcc
	v_cmp_ge_u32_e32 vcc, v5, v2
	v_add_u32_e32 v5, 1, v3
	v_add_u32_e32 v6, 1, v4
	v_cndmask_b32_e32 v3, v3, v5, vcc
	v_mad_u64_u32 v[4:5], s[0:1], v2, v3, v[2:3]
	v_cmp_ne_u32_e32 vcc, v6, v4
	s_and_saveexec_b64 s[0:1], vcc
	s_xor_b64 s[0:1], exec, s[0:1]
	s_cbranch_execz .LBB0_420
	v_mov_b32_e32 v0, s3
	v_add_co_u32_e32 v4, vcc, 0x2000, v0
	v_mov_b32_e32 v0, s2
	s_nop 0
	v_addc_co_u32_e32 v5, vcc, 0, v0, vcc
	flat_load_dword v0, v[4:5] offset:1024 sc1
	s_add_u32 s6, s3, 0x2400
	s_addc_u32 s7, s2, 0
	s_waitcnt vmcnt(0) lgkmcnt(0)
	v_cmp_eq_u32_e32 vcc, v0, v3
	s_and_saveexec_b64 s[4:5], vcc
	s_cbranch_execz .LBB0_419
	s_add_u32 s8, s58, 0x22f20200
	s_addc_u32 s9, s59, 0
	s_mov_b32 s24, 1
	s_mov_b64 s[10:11], 0
	s_branch .LBB0_411

; DI unsigned xb_ld(unsigned* p) { return __hip_atomic_load(p, __ATOMIC_RELAXED, __HIP_MEMORY_SCOPE_AGENT); }
; DI unsigned xb_add(unsigned* p, unsigned v) { return __hip_atomic_fetch_add(p, v, __ATOMIC_RELAXED, __HIP_MEMORY_SCOPE_AGENT); }
; #define XB_SPIN(cond, bar) do { unsigned _sp = 0; while (cond) { __builtin_amdgcn_s_sleep(1); \
;     if ((++_sp & 255u) == 0u) { if (xb_ld(&(bar)[XB_TMO])) break; if (_sp > XB_SPIN_CAP) { atomicAdd(&(bar)[XB_TMO], 1u); break; } } } } while (0)
; DI void xcd_barrier(unsigned* bar, volatile LAS unsigned* st) {
;     ...
;     const unsigned old = xb_add(&bar[XB_XSUB(x)], 1u);
;     const unsigned gen = old / nloc;
;     if (old + 1u == (gen + 1u) * nloc) {
;       __builtin_amdgcn_fence(__ATOMIC_RELEASE, "agent");
;       asm volatile("s_waitcnt vmcnt(0)" ::: "memory");
;       const unsigned og = xb_add(&bar[XB_TOP], 1u);
;       const unsigned tg = og / nx;
;       if (og + 1u == (tg + 1u) * nx) xb_add(&bar[XB_TOPGEN], 1u);
;       else XB_SPIN(xb_ld(&bar[XB_TOPGEN]) == tg, bar);
;       __builtin_amdgcn_fence(__ATOMIC_ACQUIRE, "agent");
;       xb_add(&bar[XB_XGEN(x)], 1u);
;       asm volatile("s_waitcnt vmcnt(0)" ::: "memory");
;     } else {
;       XB_SPIN(xb_ld(&bar[XB_XGEN(x)]) == gen, bar);
.LBB0_544:
	s_lshl_b32 s0, s3, 8
	s_add_u32 s0, s58, s0
	s_addc_u32 s1, s59, 0
	v_mov_b32_e32 v3, s0
	v_add_co_u32_e32 v4, vcc, 0x22f21000, v3
	v_mov_b32_e32 v3, s1
	s_nop 0
	v_addc_co_u32_e32 v5, vcc, 0, v3, vcc
	flat_atomic_add v4, v[4:5], v187 offset:1024 sc0
	buffer_inv sc1
	v_cvt_f32_u32_e32 v3, v2
	v_sub_u32_e32 v5, 0, v2
	s_add_u32 s24, s0, 0x22f20000
	s_addc_u32 s3, s1, 0
	v_rcp_iflag_f32_e32 v3, v3
	s_nop 0
	v_mul_f32_e32 v3, 0x4f7ffffe, v3
	v_cvt_u32_f32_e32 v3, v3
	v_mul_lo_u32 v5, v5, v3
	v_mul_hi_u32 v5, v3, v5
	v_add_u32_e32 v3, v3, v5
	s_waitcnt vmcnt(0) lgkmcnt(0)
	v_mul_hi_u32 v3, v4, v3
	v_mul_lo_u32 v5, v3, v2
	v_sub_u32_e32 v5, v4, v5
	v_cmp_ge_u32_e32 vcc, v5, v2
	v_add_u32_e32 v6, 1, v3
	s_nop 0
	v_cndmask_b32_e32 v3, v3, v6, vcc
	v_sub_u32_e32 v6, v5, v2
	v_cndmask_b32_e32 v5, v5, v6, vcc
	v_cmp_ge_u32_e32 vcc, v5, v2
	v_add_u32_e32 v5, 1, v3
	v_add_u32_e32 v6, 1, v4
	v_cndmask_b32_e32 v3, v3, v5, vcc
	v_mad_u64_u32 v[4:5], s[0:1], v2, v3, v[2:3]
	v_cmp_ne_u32_e32 vcc, v6, v4
	s_and_saveexec_b64 s[0:1], vcc
	s_xor_b64 s[0:1], exec, s[0:1]
	s_cbranch_execz .LBB0_557
	v_mov_b32_e32 v0, s24
	v_add_co_u32_e32 v4, vcc, 0x2000, v0
	v_mov_b32_e32 v0, s3
	s_nop 0
	v_addc_co_u32_e32 v5, vcc, 0, v0, vcc
	flat_load_dword v0, v[4:5] offset:1024 sc1
	s_add_u32 s6, s24, 0x2400
	s_addc_u32 s7, s3, 0
	s_waitcnt vmcnt(0) lgkmcnt(0)
	v_cmp_eq_u32_e32 vcc, v0, v3
	s_and_saveexec_b64 s[4:5], vcc
	s_cbranch_execz .LBB0_556
	s_add_u32 s8, s58, 0x22f20200
	s_addc_u32 s9, s59, 0
	s_mov_b32 s25, 1
	s_mov_b64 s[10:11], 0
	s_branch .LBB0_548

; DI unsigned xb_add(unsigned* p, unsigned v) { return __hip_atomic_fetch_add(p, v, __ATOMIC_RELAXED, __HIP_MEMORY_SCOPE_AGENT); }
; DI void xcd_barrier(unsigned* bar, volatile LAS unsigned* st) {
;     ...
;       __builtin_amdgcn_fence(__ATOMIC_ACQUIRE, "agent");
;       xb_add(&bar[XB_XGEN(x)], 1u);
;       asm volatile("s_waitcnt vmcnt(0)" ::: "memory");
.LBB0_572:
	s_or_b64 exec, exec, s[0:1]
	v_mov_b32_e32 v0, s24
	v_add_co_u32_e32 v2, vcc, 0x2000, v0
	v_mov_b32_e32 v0, s3
	s_nop 0
	v_addc_co_u32_e32 v3, vcc, 0, v0, vcc
	s_waitcnt vmcnt(0) lgkmcnt(0)
	flat_atomic_add v[2:3], v187 offset:1024
	s_waitcnt vmcnt(0)

; DI unsigned xb_ld(unsigned* p) { return __hip_atomic_load(p, __ATOMIC_RELAXED, __HIP_MEMORY_SCOPE_AGENT); }
; DI unsigned xb_add(unsigned* p, unsigned v) { return __hip_atomic_fetch_add(p, v, __ATOMIC_RELAXED, __HIP_MEMORY_SCOPE_AGENT); }
; #define XB_SPIN(cond, bar) do { unsigned _sp = 0; while (cond) { __builtin_amdgcn_s_sleep(1); \
;     if ((++_sp & 255u) == 0u) { if (xb_ld(&(bar)[XB_TMO])) break; if (_sp > XB_SPIN_CAP) { atomicAdd(&(bar)[XB_TMO], 1u); break; } } } } while (0)
; DI void xcd_barrier(unsigned* bar, volatile LAS unsigned* st) {
;     ...
;     const unsigned old = xb_add(&bar[XB_XSUB(x)], 1u);
;     const unsigned gen = old / nloc;
;     if (old + 1u == (gen + 1u) * nloc) {
;       __builtin_amdgcn_fence(__ATOMIC_RELEASE, "agent");
;       asm volatile("s_waitcnt vmcnt(0)" ::: "memory");
;       const unsigned og = xb_add(&bar[XB_TOP], 1u);
;       const unsigned tg = og / nx;
;       if (og + 1u == (tg + 1u) * nx) xb_add(&bar[XB_TOPGEN], 1u);
;       else XB_SPIN(xb_ld(&bar[XB_TOPGEN]) == tg, bar);
;       __builtin_amdgcn_fence(__ATOMIC_ACQUIRE, "agent");
;       xb_add(&bar[XB_XGEN(x)], 1u);
;       asm volatile("s_waitcnt vmcnt(0)" ::: "memory");
;     } else {
;       XB_SPIN(xb_ld(&bar[XB_XGEN(x)]) == gen, bar);
.LBB0_848:
	s_lshl_b32 s0, s2, 8
	s_add_u32 s0, s40, s0
	s_addc_u32 s1, s41, 0
	v_mov_b32_e32 v3, s0
	v_add_co_u32_e32 v4, vcc, 0x22f21000, v3
	v_mov_b32_e32 v3, s1
	s_nop 0
	v_addc_co_u32_e32 v5, vcc, 0, v3, vcc
	flat_atomic_add v4, v[4:5], v187 offset:1024 sc0
	buffer_inv sc1
	v_cvt_f32_u32_e32 v3, v2
	v_sub_u32_e32 v5, 0, v2
	s_add_u32 s3, s0, 0x22f20000
	s_addc_u32 s2, s1, 0
	v_rcp_iflag_f32_e32 v3, v3
	s_nop 0
	v_mul_f32_e32 v3, 0x4f7ffffe, v3
	v_cvt_u32_f32_e32 v3, v3
	v_mul_lo_u32 v5, v5, v3
	v_mul_hi_u32 v5, v3, v5
	v_add_u32_e32 v3, v3, v5
	s_waitcnt vmcnt(0) lgkmcnt(0)
	v_mul_hi_u32 v3, v4, v3
	v_mul_lo_u32 v5, v3, v2
	v_sub_u32_e32 v5, v4, v5
	v_cmp_ge_u32_e32 vcc, v5, v2
	v_add_u32_e32 v6, 1, v3
	s_nop 0
	v_cndmask_b32_e32 v3, v3, v6, vcc
	v_sub_u32_e32 v6, v5, v2
	v_cndmask_b32_e32 v5, v5, v6, vcc
	v_cmp_ge_u32_e32 vcc, v5, v2
	v_add_u32_e32 v5, 1, v3
	v_add_u32_e32 v6, 1, v4
	v_cndmask_b32_e32 v3, v3, v5, vcc
	v_mad_u64_u32 v[4:5], s[0:1], v2, v3, v[2:3]
	v_cmp_ne_u32_e32 vcc, v6, v4
	s_and_saveexec_b64 s[0:1], vcc
	s_xor_b64 s[0:1], exec, s[0:1]
	s_cbranch_execz .LBB0_861
	v_mov_b32_e32 v0, s3
	v_add_co_u32_e32 v4, vcc, 0x2000, v0
	v_mov_b32_e32 v0, s2
	s_nop 0
	v_addc_co_u32_e32 v5, vcc, 0, v0, vcc
	flat_load_dword v0, v[4:5] offset:1024 sc1
	s_add_u32 s6, s3, 0x2400
	s_addc_u32 s7, s2, 0
	s_waitcnt vmcnt(0) lgkmcnt(0)
	v_cmp_eq_u32_e32 vcc, v0, v3
	s_and_saveexec_b64 s[4:5], vcc
	s_cbranch_execz .LBB0_860
	s_add_u32 s8, s40, 0x22f20200
	s_addc_u32 s9, s41, 0
	s_mov_b32 s24, 1
	s_mov_b64 s[10:11], 0
	s_branch .LBB0_852
